# P0 item loops: the two independent kernarg pointer reads share one wait
# baseline (speedup 1.0000x reference)
; #define LAS __attribute__((address_space(3)))
; __device__ __forceinline__ void p0_load(const P0Item& it, f32x4 (&w)[16], int lane) {
;     const unsigned voff = (unsigned)(((lane >> 4) * it.ldw + (lane & 15) * 4) * 4);
; #pragma unroll
;     for (int i = 0; i < 16; ++i) w[i] = __builtin_nontemporal_load((const f32x4*)((const char*)(it.src + (size_t)(4 * i) * it.ldw) + voff));
; }
; __device__ __forceinline__ void p0_finish(const P0Item& it, const f32x4 (&w)[16], LAS float* scr, int lane) {
;     const int c4 = (lane & 15) * 4, kr = lane >> 4;
;     if (it.gain) { const unsigned goff = (unsigned)(kr * 4);
; #pragma unroll
;         for (int i = 0; i < 16; ++i) { const float g = *(const float*)((const char*)(it.gain + 4 * i) + goff); *(LAS f32x4*)(scr + (kr + 4 * i) * 68 + c4) = w[i] * g; } }
; __global__ void __launch_bounds__(NWAVES * 64, 2) fwd(Args args) {
;     ...
;               p0_pipe(8, [&](int i) { return p0_item(wsrc, INW, DM, gsrc, W_inT, IN_N / 64, src0, 0, (wv + 8 * i) * (IN_N / 64) + nb); }, scr, F.lane); }
.LBB0_16:
	flat_load_dwordx2 v[2:3], v[70:71] offset:24 sc0 sc1
	s_mul_hi_i32 s4, s3, 0x2aaaaaab
	s_lshr_b32 s6, s4, 31
	s_ashr_i32 s4, s4, 4
	s_add_i32 s4, s4, s6
	s_mul_i32 s6, s4, 0x60
	s_mulk_i32 s4, 0xffa0
	s_add_i32 s4, s3, s4
	s_cmp_gt_i32 s4, 63
	s_cselect_b32 s4, 64, 0
	s_add_i32 s7, s3, s6
	s_mul_hi_i32 s7, s7, 0x2aaaaaab
	s_lshr_b32 s10, s7, 31
	s_ashr_i32 s7, s7, 5
	s_add_i32 s7, s7, s10
	s_mul_i32 s11, s7, 0xc0
	s_sub_i32 s6, s6, s11
	s_add_i32 s6, s3, s6
	s_lshl_b32 s6, s6, 6
	s_lshl_b32 s10, s7, 6
	s_ashr_i32 s7, s6, 31
	v_or_b32_e32 v86, s10, v74
	v_or_b32_e32 v6, 4, v86
	v_or_b32_e32 v8, 8, v86
	v_or_b32_e32 v10, 12, v86
	v_or_b32_e32 v11, 16, v86
	v_or_b32_e32 v12, 20, v86
	v_or_b32_e32 v13, 24, v86
	v_or_b32_e32 v14, 28, v86
	v_or_b32_e32 v15, 32, v86
	v_or_b32_e32 v16, 36, v86
	v_or_b32_e32 v17, 40, v86
	v_or_b32_e32 v18, 44, v86
	v_or_b32_e32 v19, 48, v86
	v_or_b32_e32 v20, 52, v86
	v_or_b32_e32 v21, 56, v86
	flat_load_dwordx2 v[72:73], v[70:71] offset:16 sc0 sc1
	s_waitcnt vmcnt(0)
	v_or_b32_e32 v85, 60, v86
	v_ashrrev_i32_e32 v87, 31, v86
	s_waitcnt lgkmcnt(0)
	v_lshl_add_u64 v[2:3], v[2:3], 0, s[4:5]
	v_lshl_add_u64 v[2:3], s[6:7], 2, v[2:3]
	v_lshl_add_u64 v[2:3], v[2:3], 0, v[66:67]
	v_mad_i64_i32 v[4:5], s[12:13], v86, s15, v[2:3]
	v_mad_i64_i32 v[6:7], s[12:13], v6, s15, v[2:3]
	v_mad_i64_i32 v[8:9], s[12:13], v8, s15, v[2:3]
	v_mad_i64_i32 v[88:89], s[12:13], v10, s15, v[2:3]
	v_mad_i64_i32 v[90:91], s[12:13], v11, s15, v[2:3]
	v_mad_i64_i32 v[92:93], s[12:13], v12, s15, v[2:3]
	v_mad_i64_i32 v[94:95], s[12:13], v13, s15, v[2:3]
	v_mad_i64_i32 v[96:97], s[12:13], v14, s15, v[2:3]
	v_mad_i64_i32 v[98:99], s[12:13], v15, s15, v[2:3]
	v_mad_i64_i32 v[100:101], s[12:13], v16, s15, v[2:3]
	v_mad_i64_i32 v[102:103], s[12:13], v17, s15, v[2:3]
	v_mad_i64_i32 v[104:105], s[12:13], v18, s15, v[2:3]
	v_mad_i64_i32 v[106:107], s[12:13], v19, s15, v[2:3]
	v_mad_i64_i32 v[108:109], s[12:13], v20, s15, v[2:3]
	v_mad_i64_i32 v[110:111], s[12:13], v21, s15, v[2:3]
	flat_load_dwordx4 v[62:65], v[4:5] nt
	flat_load_dwordx4 v[58:61], v[6:7] nt
	flat_load_dwordx4 v[54:57], v[8:9] nt
	flat_load_dwordx4 v[50:53], v[88:89] nt
	flat_load_dwordx4 v[46:49], v[90:91] nt
	flat_load_dwordx4 v[42:45], v[92:93] nt
	flat_load_dwordx4 v[38:41], v[94:95] nt
	flat_load_dwordx4 v[34:37], v[96:97] nt
	flat_load_dwordx4 v[30:33], v[98:99] nt
	flat_load_dwordx4 v[26:29], v[100:101] nt
	flat_load_dwordx4 v[22:25], v[102:103] nt
	flat_load_dwordx4 v[18:21], v[104:105] nt
	flat_load_dwordx4 v[14:17], v[106:107] nt
	flat_load_dwordx4 v[10:13], v[108:109] nt
	v_mad_i64_i32 v[88:89], s[12:13], v85, s15, v[2:3]
	flat_load_dwordx4 v[6:9], v[110:111] nt
	flat_load_dwordx4 v[2:5], v[88:89] nt
	v_cmp_ne_u64_e32 vcc, 0, v[72:73]
	v_lshl_add_u64 v[72:73], v[86:87], 2, v[72:73]
	s_and_saveexec_b64 s[12:13], vcc
	s_xor_b64 s[12:13], exec, s[12:13]
	s_cbranch_execz .LBB0_18
	global_load_dword v220, v[72:73], off
	global_load_dword v221, v[72:73], off offset:16
	global_load_dword v222, v[72:73], off offset:32
	global_load_dword v223, v[72:73], off offset:48
	global_load_dword v224, v[72:73], off offset:64
	global_load_dword v225, v[72:73], off offset:80
	global_load_dword v226, v[72:73], off offset:96
	global_load_dword v227, v[72:73], off offset:112
	global_load_dword v228, v[72:73], off offset:128
	global_load_dword v229, v[72:73], off offset:144
	global_load_dword v230, v[72:73], off offset:160
	global_load_dword v231, v[72:73], off offset:176
	global_load_dword v232, v[72:73], off offset:192
	global_load_dword v233, v[72:73], off offset:208
	global_load_dword v234, v[72:73], off offset:224
	global_load_dword v235, v[72:73], off offset:240
	s_waitcnt vmcnt(0) lgkmcnt(0)
	v_mov_b32_e32 v86, v220
	v_pk_mul_f32 v[64:65], v[64:65], v[86:87] op_sel_hi:[1,0]
	v_pk_mul_f32 v[62:63], v[62:63], v[86:87] op_sel_hi:[1,0]
	ds_write_b128 v84, v[62:65]
	s_nop 1
	v_mov_b32_e32 v62, v221
	v_pk_mul_f32 v[60:61], v[60:61], v[62:63] op_sel_hi:[1,0]
	v_pk_mul_f32 v[58:59], v[58:59], v[62:63] op_sel_hi:[1,0]

; #define LAS __attribute__((address_space(3)))
; #define g_mix ARGP(2)
; #define w_in ARGP(3)
; __device__ __forceinline__ void p0_transpose64(const float* W, int ldw, int K, const float* gain, bf16_t* WT, int nblk, int ncol_src0, int row_off, LAS float* scr, int item, int lane) {
;     const int kb = item / nblk, nb = item % nblk, k0 = 64 * kb, n0 = 64 * nb;
;     const int c4 = (lane & 15) * 4, kr = lane >> 4;
;     f32x4 w[16];
; #pragma unroll
;     for (int i = 0; i < 16; ++i) w[i] = __builtin_nontemporal_load((const f32x4*)(W + (size_t)(k0 + kr + 4 * i) * ldw + ncol_src0 + n0 + c4));
; #pragma unroll
;     for (int i = 0; i < 16; ++i) { f32x4 v = w[i]; if (gain) v = v * gain[k0 + kr + 4 * i]; *(LAS f32x4*)(scr + (kr + 4 * i) * 68 + c4) = v; }
; __global__ void __launch_bounds__(NWAVES * 64, 2) fwd(Args args) {
;     ...
;             for (int it = (bx - NQB) * NWAVES + F.wave; it < I_INL; it += (256 - NQB) * NWAVES) { const int kb = it / (IN_Q0 / 64), nb = it % (IN_Q0 / 64);
;                 p0_transpose64(w_in, INW, DM, g_mix, W_inT, IN_N / 64, (nb * 64 >= 4096) ? 16 : 0, 0, scr, kb * (IN_N / 64) + nb, F.lane); }
.LBB0_49:
	s_andn2_b64 vcc, exec, s[4:5]
	s_cbranch_vccnz .LBB0_66
	v_mov_b64_e32 v[2:3], s[92:93]
	flat_load_dwordx2 v[66:67], v[2:3] offset:24 sc0 sc1
	s_cmpk_gt_i32 s2, 0xffdf
	s_mul_i32 s4, s46, 0xc0
	s_cselect_b32 s10, 64, 0
	s_add_i32 s15, s2, s4
	s_add_i32 s4, s15, 0x60
	s_mul_hi_i32 s5, s4, 0x2aaaaaab
	s_lshr_b32 s6, s5, 31
	s_ashr_i32 s5, s5, 5
	s_add_i32 s5, s5, s6
	v_lshrrev_b32_e32 v90, 4, v182
	s_mul_i32 s7, s5, 0xc0
	v_mov_b32_e32 v148, 0xc040
	v_and_b32_e32 v91, 60, v1
	flat_load_dwordx2 v[136:137], v[2:3] offset:16 sc0 sc1
	s_waitcnt vmcnt(0)
	v_mul_u32_u24_e32 v2, 0x3010, v90
	s_lshl_b32 s6, s5, 6
	s_sub_i32 s4, s4, s7
	s_mov_b32 s11, 0
	v_add_lshl_u32 v134, v2, v91, 2
	s_lshl_b32 s4, s4, 6
	s_ashr_i32 s5, s4, 31
	v_mov_b32_e32 v135, 0
	s_mov_b32 s3, 0x30000
	s_mov_b32 s22, 0x60000
	s_mov_b32 s23, 0x90000
	s_mov_b32 s24, 0xc0000
	s_mov_b32 s25, 0xf0000
	s_mov_b32 s26, 0x120000
	s_mov_b32 s27, 0x150000
	s_mov_b32 s28, 0x180000
	s_mov_b32 s29, 0x1b0000
	s_mov_b32 s30, 0x1e0000
	s_mov_b32 s31, 0x210000
	s_mov_b32 s33, 0x240000
	s_mov_b32 s7, 0x270000
	v_lshlrev_b32_e32 v138, 2, v90
	v_mov_b32_e32 v139, v135
	v_mov_b32_e32 v141, v135
	s_mov_b32 s34, 0x10000
	s_mov_b32 s35, 0x20000
	s_mov_b32 s36, 0x40000
	s_mov_b32 s37, 0x50000
	s_waitcnt lgkmcnt(0)
	v_mad_i64_i32 v[2:3], s[12:13], s6, v148, v[66:67]
	v_lshl_add_u64 v[2:3], v[2:3], 0, s[10:11]
	v_lshl_add_u64 v[2:3], s[4:5], 2, v[2:3]
	v_lshl_add_u64 v[18:19], v[2:3], 0, v[134:135]
	v_add_co_u32_e32 v20, vcc, s3, v18
	s_lshl_b64 s[4:5], s[4:5], 13
	s_nop 0
	v_addc_co_u32_e32 v21, vcc, 0, v19, vcc
	v_add_co_u32_e32 v22, vcc, s22, v18
	v_lshl_add_u64 v[142:143], v[66:67], 0, s[10:11]
	s_nop 0
	v_addc_co_u32_e32 v23, vcc, 0, v19, vcc
	v_add_co_u32_e32 v24, vcc, s23, v18
	v_lshl_add_u64 v[144:145], v[136:137], 0, v[138:139]
	s_nop 0
	v_addc_co_u32_e32 v25, vcc, 0, v19, vcc
	v_add_co_u32_e32 v26, vcc, s24, v18
	flat_load_dwordx4 v[2:5], v[18:19] nt
	flat_load_dwordx4 v[6:9], v[20:21] offset:256 nt
	flat_load_dwordx4 v[10:13], v[22:23] offset:512 nt
	flat_load_dwordx4 v[14:17], v[24:25] offset:768 nt
	v_addc_co_u32_e32 v27, vcc, 0, v19, vcc
	v_add_co_u32_e32 v68, vcc, s25, v18
	s_nop 1
	v_addc_co_u32_e32 v69, vcc, 0, v19, vcc
	v_add_co_u32_e32 v70, vcc, s26, v18
	s_nop 1
	v_addc_co_u32_e32 v71, vcc, 0, v19, vcc
	v_add_co_u32_e32 v72, vcc, s27, v18
	s_nop 1
	v_addc_co_u32_e32 v73, vcc, 0, v19, vcc
	v_add_co_u32_e32 v74, vcc, s28, v18
	s_nop 1
	v_addc_co_u32_e32 v75, vcc, 0, v19, vcc
	v_add_co_u32_e32 v76, vcc, s29, v18
	s_nop 1
	v_addc_co_u32_e32 v77, vcc, 0, v19, vcc
	v_add_co_u32_e32 v78, vcc, s30, v18
	s_nop 1
	v_addc_co_u32_e32 v79, vcc, 0, v19, vcc
	v_add_co_u32_e32 v80, vcc, s31, v18
	s_nop 1
	v_addc_co_u32_e32 v81, vcc, 0, v19, vcc
	v_add_co_u32_e32 v82, vcc, s33, v18
	s_nop 1
	v_addc_co_u32_e32 v83, vcc, 0, v19, vcc
	v_add_co_u32_e32 v84, vcc, s7, v18
	s_mov_b32 s7, 0x2a0000
	s_nop 0
	v_addc_co_u32_e32 v85, vcc, 0, v19, vcc
	v_add_co_u32_e32 v86, vcc, s7, v18
	s_mov_b32 s7, 0x2d0000
	s_nop 0
	v_addc_co_u32_e32 v87, vcc, 0, v19, vcc
	v_add_co_u32_e32 v88, vcc, s7, v18
	s_ashr_i32 s7, s6, 31
	s_nop 0
	v_addc_co_u32_e32 v89, vcc, 0, v19, vcc
	flat_load_dwordx4 v[18:21], v[26:27] offset:1024 nt
	flat_load_dwordx4 v[22:25], v[68:69] offset:1280 nt
	s_nop 0
	flat_load_dwordx4 v[26:29], v[70:71] offset:1536 nt
	flat_load_dwordx4 v[30:33], v[72:73] offset:1792 nt
	flat_load_dwordx4 v[34:37], v[74:75] offset:2048 nt
	flat_load_dwordx4 v[38:41], v[76:77] offset:2304 nt
	flat_load_dwordx4 v[42:45], v[78:79] offset:2560 nt
	flat_load_dwordx4 v[46:49], v[80:81] offset:2816 nt
	flat_load_dwordx4 v[50:53], v[82:83] offset:3072 nt
	flat_load_dwordx4 v[54:57], v[84:85] offset:3328 nt
	flat_load_dwordx4 v[58:61], v[86:87] offset:3584 nt
	flat_load_dwordx4 v[62:65], v[88:89] offset:3840 nt
	s_add_u32 s12, s72, s4
	v_lshlrev_b32_e32 v71, 3, v0
	s_addc_u32 s13, s73, s5
	s_lshl_b64 s[4:5], s[6:7], 1
	v_lshl_add_u64 v[68:69], s[6:7], 2, v[136:137]
	v_cmp_eq_u64_e64 s[6:7], 0, v[136:137]
	v_lshrrev_b32_e32 v70, 3, v182
	v_and_b32_e32 v71, 56, v71
	s_add_u32 s12, s12, s4
	v_cndmask_b32_e64 v147, v69, 0, s[6:7]
	v_cndmask_b32_e64 v146, v68, 0, s[6:7]
	v_lshl_add_u32 v68, v91, 2, s14
	v_mul_u32_u24_e32 v69, 0x110, v90
	v_mul_u32_u24_e32 v72, 0x110, v71
	v_lshlrev_b32_e32 v73, 2, v70
	v_lshlrev_b32_e32 v70, 13, v70
	s_addc_u32 s13, s13, s5
	v_cmp_ne_u64_e64 s[4:5], 0, v[136:137]
	v_add3_u32 v149, s14, v72, v73
	v_and_b32_e32 v248, 7, v182
	v_mul_u32_u24_e32 v248, 0x770, v248
	v_sub_u32_e32 v149, v149, v248
	v_lshl_or_b32 v140, v71, 1, v70
	s_add_i32 s10, s15, 0xc60
	v_add_u32_e32 v150, v68, v69
	v_lshrrev_b32_e32 v248, 4, v182
	v_mul_u32_u24_e32 v248, 0x770, v248
	v_add_u32_e32 v150, v150, v248
	s_branch .LBB0_52
